# v61 + counted lgkmcnt(2) before the first 8 MFMAs of waves 0-3 (wait at first consumer)
# baseline (speedup 1.0000x reference)
; template <int MODE, bool SWAP, int MT>
; DI void gemm_tile(const int wv_, const Params& p, const u16* __restrict__ A, const u16* __restrict__ Bt, int brow, int bcol, char* smem, const float* gnext) {
;     ...
;     asm volatile("s_waitcnt vmcnt(0)" ::: "memory");
;     __syncthreads();
;     if (t + 1 < 32) stage(t + 1, (t + 1) & 1);
;     const char* sA = smem + (t & 1) * 24576; const char* sB = sA + 16384;
;     bf16x8 Af[MT], Bf[4];
; #pragma unroll
;     for (int n = 0; n < 4; ++n) Bf[n] = *(const bf16x8*)(sB + (wc * 64 + n * 16 + fr) * 64 + fq * 16);
;     constexpr int MH = MT >= 2 ? MT / 2 : 1;
; #pragma unroll
;     for (int m = 0; m < MH; ++m) Af[m] = *(const bf16x8*)(sA + (wr * (16 * MT) + m * 16 + fr) * 64 + fq * 16);
;     __builtin_amdgcn_sched_barrier(0);
; #pragma unroll
;     for (int m = MH; m < MT; ++m) Af[m] = *(const bf16x8*)(sA + (wr * (16 * MT) + m * 16 + fr) * 64 + fq * 16);
; #pragma unroll
;     for (int m = 0; m < MH; ++m)
; #pragma unroll
;       for (int n = 0; n < 4; ++n)
;         acc[m][n] = SWAP ? __builtin_amdgcn_mfma_f32_16x16x32_bf16(Bf[n], Af[m], acc[m][n], 0, 0, 0)
;                          : __builtin_amdgcn_mfma_f32_16x16x32_bf16(Af[m], Bf[n], acc[m][n], 0, 0, 0);
.LBB0_86:
	s_add_i32 s1, s0, 1
	s_waitcnt lgkmcnt(2)
	v_mfma_f32_16x16x32_bf16 v[64:67], v[80:83], v[96:99], v[64:67]
	v_mfma_f32_16x16x32_bf16 v[60:63], v[84:87], v[96:99], v[60:63]
	v_mfma_f32_16x16x32_bf16 v[56:59], v[88:91], v[96:99], v[56:59]
	v_mfma_f32_16x16x32_bf16 v[52:55], v[92:95], v[96:99], v[52:55]
	v_mfma_f32_16x16x32_bf16 v[48:51], v[80:83], v[100:103], v[48:51]
	v_mfma_f32_16x16x32_bf16 v[40:43], v[84:87], v[100:103], v[40:43]
	v_mfma_f32_16x16x32_bf16 v[36:39], v[88:91], v[100:103], v[36:39]
	v_mfma_f32_16x16x32_bf16 v[44:47], v[92:95], v[100:103], v[44:47]
	s_cmp_gt_u32 s0, 29
	s_cbranch_scc1 .Lpp_last_1
	s_waitcnt vmcnt(3) lgkmcnt(0)
	s_barrier
	s_cmp_gt_u32 s0, 28
	s_cbranch_scc1 .Lpp_nodma_1
	s_add_i32 s101, s98, s99
	s_mov_b32 m0, s101
	s_add_i32 s101, s101, 0x2000
	global_load_lds_dwordx4 v[0:1], off
	s_mov_b32 m0, s101
	s_add_i32 s101, s101, 0x2000
	global_load_lds_dwordx4 v[68:69], off
	s_mov_b32 m0, s101
	s_add_i32 s99, s99, 0x6000
	global_load_lds_dwordx4 v[70:71], off
	s_cmp_eq_u32 s99, 0x12000
	s_cselect_b32 s99, 0, s99
	v_lshl_add_u64 v[0:1], v[0:1], 0, 64
	v_lshl_add_u64 v[68:69], v[68:69], 0, 64
	v_lshl_add_u64 v[70:71], v[70:71], 0, 64

; template <int MODE, bool SWAP, int MT>
; DI void gemm_tile(const int wv_, const Params& p, const u16* __restrict__ A, const u16* __restrict__ Bt, int brow, int bcol, char* smem, const float* gnext) {
;     ...
; #pragma unroll
;     for (int m = MH; m < MT; ++m)
; #pragma unroll
;       for (int n = 0; n < 4; ++n)
;         acc[m][n] = SWAP ? __builtin_amdgcn_mfma_f32_16x16x32_bf16(Bf[n], Af[m], acc[m][n], 0, 0, 0)
;                          : __builtin_amdgcn_mfma_f32_16x16x32_bf16(Af[m], Bf[n], acc[m][n], 0, 0, 0);
.Lpp_last_1:
	s_waitcnt lgkmcnt(0)
	v_mfma_f32_16x16x32_bf16 v[32:35], v[80:83], v[104:107], v[32:35]
	v_mfma_f32_16x16x32_bf16 v[28:31], v[84:87], v[104:107], v[28:31]
	v_mfma_f32_16x16x32_bf16 v[24:27], v[88:91], v[104:107], v[24:27]
	v_mfma_f32_16x16x32_bf16 v[20:23], v[92:95], v[104:107], v[20:23]
	v_mfma_f32_16x16x32_bf16 v[16:19], v[80:83], v[108:111], v[16:19]
	v_mfma_f32_16x16x32_bf16 v[12:15], v[84:87], v[108:111], v[12:15]
	v_mfma_f32_16x16x32_bf16 v[8:11], v[88:91], v[108:111], v[8:11]
	v_mfma_f32_16x16x32_bf16 v[4:7], v[92:95], v[108:111], v[4:7]
	s_mov_b32 s0, s1
	s_branch .Lpp_exit_1

; template <int MODE, bool SWAP, int MT>
; DI void gemm_tile(const int wv_, const Params& p, const u16* __restrict__ A, const u16* __restrict__ Bt, int brow, int bcol, char* smem, const float* gnext) {
;     ...
;     asm volatile("s_waitcnt vmcnt(0)" ::: "memory");
;     __syncthreads();
;     if (t + 1 < 32) stage(t + 1, (t + 1) & 1);
;     const char* sA = smem + (t & 1) * 24576; const char* sB = sA + 16384;
;     bf16x8 Af[MT], Bf[4];
; #pragma unroll
;     for (int n = 0; n < 4; ++n) Bf[n] = *(const bf16x8*)(sB + (wc * 64 + n * 16 + fr) * 64 + fq * 16);
;     constexpr int MH = MT >= 2 ? MT / 2 : 1;
; #pragma unroll
;     for (int m = 0; m < MH; ++m) Af[m] = *(const bf16x8*)(sA + (wr * (16 * MT) + m * 16 + fr) * 64 + fq * 16);
;     __builtin_amdgcn_sched_barrier(0);
; #pragma unroll
;     for (int m = MH; m < MT; ++m) Af[m] = *(const bf16x8*)(sA + (wr * (16 * MT) + m * 16 + fr) * 64 + fq * 16);
; #pragma unroll
;     for (int m = 0; m < MH; ++m)
; #pragma unroll
;       for (int n = 0; n < 4; ++n)
;         acc[m][n] = SWAP ? __builtin_amdgcn_mfma_f32_16x16x32_bf16(Bf[n], Af[m], acc[m][n], 0, 0, 0)
;                          : __builtin_amdgcn_mfma_f32_16x16x32_bf16(Af[m], Bf[n], acc[m][n], 0, 0, 0);
.LBB0_90:
	s_add_i32 s1, s0, 1
	s_waitcnt lgkmcnt(2)
	v_mfma_f32_16x16x32_bf16 v[64:67], v[96:99], v[80:83], v[64:67]
	v_mfma_f32_16x16x32_bf16 v[60:63], v[96:99], v[84:87], v[60:63]
	v_mfma_f32_16x16x32_bf16 v[56:59], v[96:99], v[88:91], v[56:59]
	v_mfma_f32_16x16x32_bf16 v[52:55], v[96:99], v[92:95], v[52:55]
	v_mfma_f32_16x16x32_bf16 v[48:51], v[100:103], v[80:83], v[48:51]
	v_mfma_f32_16x16x32_bf16 v[44:47], v[100:103], v[84:87], v[44:47]
	v_mfma_f32_16x16x32_bf16 v[40:43], v[100:103], v[88:91], v[40:43]
	v_mfma_f32_16x16x32_bf16 v[36:39], v[100:103], v[92:95], v[36:39]
	s_cmp_gt_u32 s0, 29
	s_cbranch_scc1 .Lpp_last_2
	s_waitcnt vmcnt(3) lgkmcnt(0)
	s_barrier
	s_cmp_gt_u32 s0, 28
	s_cbranch_scc1 .Lpp_nodma_2
	s_add_i32 s101, s98, s99
	s_mov_b32 m0, s101
	s_add_i32 s101, s101, 0x2000
	global_load_lds_dwordx4 v[0:1], off
	s_mov_b32 m0, s101
	s_add_i32 s101, s101, 0x2000
	global_load_lds_dwordx4 v[68:69], off
	s_mov_b32 m0, s101
	s_add_i32 s99, s99, 0x6000
	global_load_lds_dwordx4 v[70:71], off
	s_cmp_eq_u32 s99, 0x12000
	s_cselect_b32 s99, 0, s99
	v_lshl_add_u64 v[0:1], v[0:1], 0, 64
	v_lshl_add_u64 v[68:69], v[68:69], 0, 64
	v_lshl_add_u64 v[70:71], v[70:71], 0, 64

; template <int MODE, bool SWAP, int MT>
; DI void gemm_tile(const int wv_, const Params& p, const u16* __restrict__ A, const u16* __restrict__ Bt, int brow, int bcol, char* smem, const float* gnext) {
;     ...
; #pragma unroll
;     for (int m = MH; m < MT; ++m)
; #pragma unroll
;       for (int n = 0; n < 4; ++n)
;         acc[m][n] = SWAP ? __builtin_amdgcn_mfma_f32_16x16x32_bf16(Bf[n], Af[m], acc[m][n], 0, 0, 0)
;                          : __builtin_amdgcn_mfma_f32_16x16x32_bf16(Af[m], Bf[n], acc[m][n], 0, 0, 0);
.Lpp_last_2:
	s_waitcnt lgkmcnt(0)
	v_mfma_f32_16x16x32_bf16 v[32:35], v[104:107], v[80:83], v[32:35]
	v_mfma_f32_16x16x32_bf16 v[28:31], v[104:107], v[84:87], v[28:31]
	v_mfma_f32_16x16x32_bf16 v[24:27], v[104:107], v[88:91], v[24:27]
	v_mfma_f32_16x16x32_bf16 v[20:23], v[104:107], v[92:95], v[20:23]
	v_mfma_f32_16x16x32_bf16 v[16:19], v[108:111], v[80:83], v[16:19]
	v_mfma_f32_16x16x32_bf16 v[12:15], v[108:111], v[84:87], v[12:15]
	v_mfma_f32_16x16x32_bf16 v[8:11], v[108:111], v[88:91], v[8:11]
	v_mfma_f32_16x16x32_bf16 v[4:7], v[108:111], v[92:95], v[4:7]
	s_mov_b32 s0, s1
	s_branch .Lpp_exit_2

; template <int MODE, bool SWAP, int MT>
; DI void gemm_tile(const int wv_, const Params& p, const u16* __restrict__ A, const u16* __restrict__ Bt, int brow, int bcol, char* smem, const float* gnext) {
;     ...
;     asm volatile("s_waitcnt vmcnt(0)" ::: "memory");
;     __syncthreads();
;     if (t + 1 < 32) stage(t + 1, (t + 1) & 1);
;     const char* sA = smem + (t & 1) * 24576; const char* sB = sA + 16384;
;     bf16x8 Af[MT], Bf[4];
; #pragma unroll
;     for (int n = 0; n < 4; ++n) Bf[n] = *(const bf16x8*)(sB + (wc * 64 + n * 16 + fr) * 64 + fq * 16);
;     constexpr int MH = MT >= 2 ? MT / 2 : 1;
; #pragma unroll
;     for (int m = 0; m < MH; ++m) Af[m] = *(const bf16x8*)(sA + (wr * (16 * MT) + m * 16 + fr) * 64 + fq * 16);
;     __builtin_amdgcn_sched_barrier(0);
; #pragma unroll
;     for (int m = MH; m < MT; ++m) Af[m] = *(const bf16x8*)(sA + (wr * (16 * MT) + m * 16 + fr) * 64 + fq * 16);
; #pragma unroll
;     for (int m = 0; m < MH; ++m)
; #pragma unroll
;       for (int n = 0; n < 4; ++n)
;         acc[m][n] = SWAP ? __builtin_amdgcn_mfma_f32_16x16x32_bf16(Bf[n], Af[m], acc[m][n], 0, 0, 0)
;                          : __builtin_amdgcn_mfma_f32_16x16x32_bf16(Af[m], Bf[n], acc[m][n], 0, 0, 0);
.LBB0_373:
	s_add_i32 s6, s1, 1
	s_waitcnt lgkmcnt(2)
	v_mfma_f32_16x16x32_bf16 v[64:67], v[80:83], v[96:99], v[64:67]
	v_mfma_f32_16x16x32_bf16 v[60:63], v[84:87], v[96:99], v[60:63]
	v_mfma_f32_16x16x32_bf16 v[56:59], v[88:91], v[96:99], v[56:59]
	v_mfma_f32_16x16x32_bf16 v[52:55], v[92:95], v[96:99], v[52:55]
	v_mfma_f32_16x16x32_bf16 v[48:51], v[80:83], v[100:103], v[48:51]
	v_mfma_f32_16x16x32_bf16 v[40:43], v[84:87], v[100:103], v[40:43]
	v_mfma_f32_16x16x32_bf16 v[36:39], v[88:91], v[100:103], v[36:39]
	v_mfma_f32_16x16x32_bf16 v[44:47], v[92:95], v[100:103], v[44:47]
	s_cmp_gt_u32 s1, 29
	s_cbranch_scc1 .Lpp_last_3
	s_waitcnt vmcnt(3) lgkmcnt(0)
	s_barrier
	s_cmp_gt_u32 s1, 28
	s_cbranch_scc1 .Lpp_nodma_3
	s_add_i32 s101, s98, s99
	s_mov_b32 m0, s101
	s_add_i32 s101, s101, 0x2000
	global_load_lds_dwordx4 v[0:1], off
	s_mov_b32 m0, s101
	s_add_i32 s101, s101, 0x2000
	global_load_lds_dwordx4 v[68:69], off
	s_mov_b32 m0, s101
	s_add_i32 s99, s99, 0x6000
	global_load_lds_dwordx4 v[70:71], off
	s_cmp_eq_u32 s99, 0x12000
	s_cselect_b32 s99, 0, s99
	v_lshl_add_u64 v[0:1], v[0:1], 0, 64
	v_lshl_add_u64 v[68:69], v[68:69], 0, 64
	v_lshl_add_u64 v[70:71], v[70:71], 0, 64

; template <int MODE, bool SWAP, int MT>
; DI void gemm_tile(const int wv_, const Params& p, const u16* __restrict__ A, const u16* __restrict__ Bt, int brow, int bcol, char* smem, const float* gnext) {
;     ...
; #pragma unroll
;     for (int m = MH; m < MT; ++m)
; #pragma unroll
;       for (int n = 0; n < 4; ++n)
;         acc[m][n] = SWAP ? __builtin_amdgcn_mfma_f32_16x16x32_bf16(Bf[n], Af[m], acc[m][n], 0, 0, 0)
;                          : __builtin_amdgcn_mfma_f32_16x16x32_bf16(Af[m], Bf[n], acc[m][n], 0, 0, 0);
.Lpp_last_3:
	s_waitcnt lgkmcnt(0)
	v_mfma_f32_16x16x32_bf16 v[32:35], v[80:83], v[104:107], v[32:35]
	v_mfma_f32_16x16x32_bf16 v[28:31], v[84:87], v[104:107], v[28:31]
	v_mfma_f32_16x16x32_bf16 v[24:27], v[88:91], v[104:107], v[24:27]
	v_mfma_f32_16x16x32_bf16 v[20:23], v[92:95], v[104:107], v[20:23]
	v_mfma_f32_16x16x32_bf16 v[16:19], v[80:83], v[108:111], v[16:19]
	v_mfma_f32_16x16x32_bf16 v[12:15], v[84:87], v[108:111], v[12:15]
	v_mfma_f32_16x16x32_bf16 v[8:11], v[88:91], v[108:111], v[8:11]
	v_mfma_f32_16x16x32_bf16 v[4:7], v[92:95], v[108:111], v[4:7]
	s_mov_b32 s1, s6
	s_branch .Lpp_exit_3

; template <int MODE, bool SWAP, int MT>
; DI void gemm_tile(const int wv_, const Params& p, const u16* __restrict__ A, const u16* __restrict__ Bt, int brow, int bcol, char* smem, const float* gnext) {
;     ...
;     asm volatile("s_waitcnt vmcnt(0)" ::: "memory");
;     __syncthreads();
;     if (t + 1 < 32) stage(t + 1, (t + 1) & 1);
;     const char* sA = smem + (t & 1) * 24576; const char* sB = sA + 16384;
;     bf16x8 Af[MT], Bf[4];
; #pragma unroll
;     for (int n = 0; n < 4; ++n) Bf[n] = *(const bf16x8*)(sB + (wc * 64 + n * 16 + fr) * 64 + fq * 16);
;     constexpr int MH = MT >= 2 ? MT / 2 : 1;
; #pragma unroll
;     for (int m = 0; m < MH; ++m) Af[m] = *(const bf16x8*)(sA + (wr * (16 * MT) + m * 16 + fr) * 64 + fq * 16);
;     __builtin_amdgcn_sched_barrier(0);
; #pragma unroll
;     for (int m = MH; m < MT; ++m) Af[m] = *(const bf16x8*)(sA + (wr * (16 * MT) + m * 16 + fr) * 64 + fq * 16);
; #pragma unroll
;     for (int m = 0; m < MH; ++m)
; #pragma unroll
;       for (int n = 0; n < 4; ++n)
;         acc[m][n] = SWAP ? __builtin_amdgcn_mfma_f32_16x16x32_bf16(Bf[n], Af[m], acc[m][n], 0, 0, 0)
;                          : __builtin_amdgcn_mfma_f32_16x16x32_bf16(Af[m], Bf[n], acc[m][n], 0, 0, 0);
.LBB0_829:
	s_add_i32 s2, s1, 1
	s_waitcnt lgkmcnt(2)
	v_mfma_f32_16x16x32_bf16 v[64:67], v[80:83], v[96:99], v[64:67]
	v_mfma_f32_16x16x32_bf16 v[60:63], v[84:87], v[96:99], v[60:63]
	v_mfma_f32_16x16x32_bf16 v[56:59], v[88:91], v[96:99], v[56:59]
	v_mfma_f32_16x16x32_bf16 v[52:55], v[92:95], v[96:99], v[52:55]
	v_mfma_f32_16x16x32_bf16 v[48:51], v[80:83], v[100:103], v[48:51]
	v_mfma_f32_16x16x32_bf16 v[44:47], v[84:87], v[100:103], v[44:47]
	v_mfma_f32_16x16x32_bf16 v[40:43], v[88:91], v[100:103], v[40:43]
	v_mfma_f32_16x16x32_bf16 v[36:39], v[92:95], v[100:103], v[36:39]
	s_cmp_gt_u32 s1, 29
	s_cbranch_scc1 .Lpp_last_4
	s_waitcnt vmcnt(3) lgkmcnt(0)
	s_barrier
	s_cmp_gt_u32 s1, 28
	s_cbranch_scc1 .Lpp_nodma_4
	s_add_i32 s101, s98, s99
	s_mov_b32 m0, s101
	s_add_i32 s101, s101, 0x2000
	global_load_lds_dwordx4 v[0:1], off
	s_mov_b32 m0, s101
	s_add_i32 s101, s101, 0x2000
	global_load_lds_dwordx4 v[68:69], off
	s_mov_b32 m0, s101
	s_add_i32 s99, s99, 0x6000
	global_load_lds_dwordx4 v[70:71], off
	s_cmp_eq_u32 s99, 0x12000
	s_cselect_b32 s99, 0, s99
	v_lshl_add_u64 v[0:1], v[0:1], 0, 64
	v_lshl_add_u64 v[68:69], v[68:69], 0, 64
	v_lshl_add_u64 v[70:71], v[70:71], 0, 64

; template <int MODE, bool SWAP, int MT>
; DI void gemm_tile(const int wv_, const Params& p, const u16* __restrict__ A, const u16* __restrict__ Bt, int brow, int bcol, char* smem, const float* gnext) {
;     ...
; #pragma unroll
;     for (int m = MH; m < MT; ++m)
; #pragma unroll
;       for (int n = 0; n < 4; ++n)
;         acc[m][n] = SWAP ? __builtin_amdgcn_mfma_f32_16x16x32_bf16(Bf[n], Af[m], acc[m][n], 0, 0, 0)
;                          : __builtin_amdgcn_mfma_f32_16x16x32_bf16(Af[m], Bf[n], acc[m][n], 0, 0, 0);
.Lpp_last_4:
	s_waitcnt lgkmcnt(0)
	v_mfma_f32_16x16x32_bf16 v[32:35], v[80:83], v[104:107], v[32:35]
	v_mfma_f32_16x16x32_bf16 v[28:31], v[84:87], v[104:107], v[28:31]
	v_mfma_f32_16x16x32_bf16 v[24:27], v[88:91], v[104:107], v[24:27]
	v_mfma_f32_16x16x32_bf16 v[20:23], v[92:95], v[104:107], v[20:23]
	v_mfma_f32_16x16x32_bf16 v[16:19], v[80:83], v[108:111], v[16:19]
	v_mfma_f32_16x16x32_bf16 v[12:15], v[84:87], v[108:111], v[12:15]
	v_mfma_f32_16x16x32_bf16 v[8:11], v[88:91], v[108:111], v[8:11]
	v_mfma_f32_16x16x32_bf16 v[4:7], v[92:95], v[108:111], v[4:7]
	s_mov_b32 s1, s2
	s_branch .Lpp_exit_4
